# MoE gate/up GEMM: next-unit gather offsets no longer drained at unit top
# speedup vs baseline: 1.0286x; 1.0044x over previous
.LBB0_1073:
	s_nop 0
	v_cndmask_b32_e64 v0, 0, 1, s[0:1]
	v_cmp_ne_u32_e64 s[2:3], 1, v0
	s_andn2_b64 vcc, exec, s[0:1]
	v_mov_b32_e32 v156, v160
	v_mov_b32_e32 v157, v142
	v_mov_b32_e32 v158, v140
	v_mov_b32_e32 v159, v138
	s_mov_b32 s99, 0
	s_cbranch_vccnz .LBB0_1075
	s_ashr_i32 s23, s22, 31
	s_lshl_b64 s[0:1], s[22:23], 10
	s_add_u32 s0, s36, s0
	s_addc_u32 s1, s37, s1
	global_load_dword v244, v148, s[0:1]
	global_load_dword v245, v149, s[0:1]
	global_load_dword v246, v149, s[0:1] offset:512
	global_load_dword v247, v148, s[0:1] offset:512
	s_mov_b32 s99, 1

.LBB0_1078:
	ds_read_b128 v[162:165], v153
	ds_read_b128 v[166:169], v153 offset:1024
	ds_read_b128 v[170:173], v153 offset:2048
	ds_read_b128 v[174:177], v153 offset:3072
	ds_read_b128 v[178:181], v154
	ds_read_b128 v[182:185], v154 offset:1024
	ds_read_b128 v[186:189], v154 offset:2048
	ds_read_b128 v[196:199], v154 offset:3072
	s_add_u32 s28, s78, s26
	s_addc_u32 s29, s79, s27
	s_add_u32 s30, s28, 0x6e00100
	s_addc_u32 s31, s29, 0
	s_add_u32 s53, s19, s26
	s_addc_u32 s54, s21, s27
	s_cmpk_eq_i32 s26, 0x700
	s_cselect_b64 vcc, -1, 0
	s_and_b64 s[28:29], vcc, exec
	s_cselect_b32 s31, s7, s31
	s_cselect_b32 s30, s6, s30
	s_cselect_b32 s29, s1, s54
	s_cselect_b32 s28, s0, s53
	v_lshl_add_u64 v[190:191], v[146:147], 0, s[26:27]
	s_add_i32 m0, s25, 0xc000
	ds_read_b128 v[200:203], v155
	ds_read_b128 v[204:207], v155 offset:1024
	ds_read_b128 v[208:211], v155 offset:2048
	ds_read_b128 v[212:215], v155 offset:3072
	ds_read_b128 v[216:219], v155 offset:4096
	ds_read_b128 v[220:223], v155 offset:5120
	ds_read_b128 v[224:227], v155 offset:6144
	ds_read_b128 v[228:231], v155 offset:7168
	global_load_lds_dwordx4 v[190:191], off
	v_lshl_add_u64 v[190:191], v[144:145], 0, s[26:27]
	s_add_i32 m0, s25, 0xe000
	s_nop 0
	global_load_lds_dwordx4 v[190:191], off
	s_waitcnt vmcnt(8)
	s_waitcnt lgkmcnt(0)
	s_barrier
	s_setprio 1
	s_waitcnt lgkmcnt(0)
	v_mfma_f32_16x16x32_bf16 v[124:127], v[162:165], v[200:203], v[124:127]
	v_mfma_f32_16x16x32_bf16 v[120:123], v[170:173], v[200:203], v[120:123]
	v_mfma_f32_16x16x32_bf16 v[108:111], v[162:165], v[208:211], v[108:111]
	v_mfma_f32_16x16x32_bf16 v[104:107], v[170:173], v[208:211], v[104:107]
	v_mfma_f32_16x16x32_bf16 v[92:95], v[162:165], v[216:219], v[92:95]
	v_mfma_f32_16x16x32_bf16 v[88:91], v[170:173], v[216:219], v[88:91]
	v_mfma_f32_16x16x32_bf16 v[76:79], v[162:165], v[224:227], v[76:79]
	v_mfma_f32_16x16x32_bf16 v[72:75], v[170:173], v[224:227], v[72:75]
	v_mfma_f32_16x16x32_bf16 v[124:127], v[166:169], v[204:207], v[124:127]
	v_mfma_f32_16x16x32_bf16 v[120:123], v[174:177], v[204:207], v[120:123]
	v_mfma_f32_16x16x32_bf16 v[108:111], v[166:169], v[212:215], v[108:111]
	v_mfma_f32_16x16x32_bf16 v[104:107], v[174:177], v[212:215], v[104:107]
	v_mfma_f32_16x16x32_bf16 v[92:95], v[166:169], v[220:223], v[92:95]
	v_mfma_f32_16x16x32_bf16 v[88:91], v[174:177], v[220:223], v[88:91]
	v_mfma_f32_16x16x32_bf16 v[76:79], v[166:169], v[228:231], v[76:79]
	v_mfma_f32_16x16x32_bf16 v[72:75], v[174:177], v[228:231], v[72:75]
	s_setprio 0
	s_setprio 1
	v_mfma_f32_16x16x32_bf16 v[116:119], v[178:181], v[200:203], v[116:119]
	v_mfma_f32_16x16x32_bf16 v[112:115], v[186:189], v[200:203], v[112:115]
	v_mfma_f32_16x16x32_bf16 v[100:103], v[178:181], v[208:211], v[100:103]
	v_mfma_f32_16x16x32_bf16 v[96:99], v[186:189], v[208:211], v[96:99]
	v_mfma_f32_16x16x32_bf16 v[84:87], v[178:181], v[216:219], v[84:87]
	v_mfma_f32_16x16x32_bf16 v[80:83], v[186:189], v[216:219], v[80:83]
	v_mfma_f32_16x16x32_bf16 v[68:71], v[178:181], v[224:227], v[68:71]
	v_mfma_f32_16x16x32_bf16 v[64:67], v[186:189], v[224:227], v[64:67]
	v_mfma_f32_16x16x32_bf16 v[116:119], v[182:185], v[204:207], v[116:119]
	v_mfma_f32_16x16x32_bf16 v[112:115], v[196:199], v[204:207], v[112:115]
	v_mfma_f32_16x16x32_bf16 v[100:103], v[182:185], v[212:215], v[100:103]
	v_mfma_f32_16x16x32_bf16 v[96:99], v[196:199], v[212:215], v[96:99]
	v_mfma_f32_16x16x32_bf16 v[84:87], v[182:185], v[220:223], v[84:87]
	v_mfma_f32_16x16x32_bf16 v[80:83], v[196:199], v[220:223], v[80:83]
	v_mfma_f32_16x16x32_bf16 v[68:71], v[182:185], v[228:231], v[68:71]
	v_mfma_f32_16x16x32_bf16 v[64:67], v[196:199], v[228:231], v[64:67]
	s_setprio 0
	s_barrier
	s_add_i32 s53, s47, s38
	v_lshl_add_u64 v[190:191], s[28:29], 0, v[128:129]
	s_mov_b32 m0, s53
	ds_read_b128 v[200:203], v155 offset:16384
	ds_read_b128 v[204:207], v155 offset:17408
	ds_read_b128 v[208:211], v155 offset:18432
	ds_read_b128 v[212:215], v155 offset:19456
	ds_read_b128 v[216:219], v155 offset:20480
	ds_read_b128 v[220:223], v155 offset:21504
	ds_read_b128 v[224:227], v155 offset:22528
	ds_read_b128 v[228:231], v155 offset:23552
	global_load_lds_dwordx4 v[190:191], off
	s_add_i32 m0, s53, 0x2000
	s_add_u32 s54, s28, 0x40000
	v_lshl_add_u64 v[232:233], s[28:29], 0, v[130:131]
	s_addc_u32 s55, s29, 0
	s_add_i32 s53, s48, s38
	global_load_lds_dwordx4 v[232:233], off
	v_lshl_add_u64 v[234:235], s[54:55], 0, v[128:129]
	s_mov_b32 m0, s53
	v_cndmask_b32_e32 v132, v160, v156, vcc
	global_load_lds_dwordx4 v[234:235], off
	v_lshl_add_u64 v[234:235], s[54:55], 0, v[130:131]
	s_add_i32 m0, s53, 0x2000
	s_nop 0
	global_load_lds_dwordx4 v[234:235], off
	s_mov_b32 m0, s25
	v_lshl_add_u64 v[234:235], s[30:31], 0, v[132:133]
	global_load_lds_dwordx4 v132, s[30:31]
	v_cndmask_b32_e32 v132, v142, v157, vcc
	s_mov_b32 m0, s39
	v_lshl_add_u64 v[236:237], s[30:31], 0, v[132:133]
	global_load_lds_dwordx4 v132, s[30:31]
	s_waitcnt vmcnt(8)
	s_cmp_eq_u32 s99, 0
	s_cbranch_scc1 .Lg7_nooff
	v_lshl_or_b32 v156, v244, 11, v150
	v_lshl_or_b32 v157, v245, 11, v150
	v_lshl_or_b32 v159, v246, 11, v150
	v_lshl_or_b32 v158, v247, 11, v150
	s_mov_b32 s99, 0
.Lg7_nooff:
	s_waitcnt lgkmcnt(0)
	s_barrier
	s_setprio 1
	s_waitcnt lgkmcnt(0)
	v_mfma_f32_16x16x32_bf16 v[60:63], v[162:165], v[200:203], v[60:63]
	v_mfma_f32_16x16x32_bf16 v[56:59], v[170:173], v[200:203], v[56:59]
	v_mfma_f32_16x16x32_bf16 v[44:47], v[162:165], v[208:211], v[44:47]
	v_mfma_f32_16x16x32_bf16 v[40:43], v[170:173], v[208:211], v[40:43]
	v_mfma_f32_16x16x32_bf16 v[28:31], v[162:165], v[216:219], v[28:31]
	v_mfma_f32_16x16x32_bf16 v[24:27], v[170:173], v[216:219], v[24:27]
	v_mfma_f32_16x16x32_bf16 v[12:15], v[162:165], v[224:227], v[12:15]
	v_mfma_f32_16x16x32_bf16 v[8:11], v[170:173], v[224:227], v[8:11]
	v_mfma_f32_16x16x32_bf16 v[60:63], v[166:169], v[204:207], v[60:63]
	v_mfma_f32_16x16x32_bf16 v[56:59], v[174:177], v[204:207], v[56:59]
	v_mfma_f32_16x16x32_bf16 v[44:47], v[166:169], v[212:215], v[44:47]
	v_mfma_f32_16x16x32_bf16 v[40:43], v[174:177], v[212:215], v[40:43]
	v_mfma_f32_16x16x32_bf16 v[28:31], v[166:169], v[220:223], v[28:31]
	v_mfma_f32_16x16x32_bf16 v[24:27], v[174:177], v[220:223], v[24:27]
	v_mfma_f32_16x16x32_bf16 v[12:15], v[166:169], v[228:231], v[12:15]
	v_mfma_f32_16x16x32_bf16 v[8:11], v[174:177], v[228:231], v[8:11]
	s_setprio 0
	s_setprio 1
	v_mfma_f32_16x16x32_bf16 v[52:55], v[178:181], v[200:203], v[52:55]
	v_mfma_f32_16x16x32_bf16 v[48:51], v[186:189], v[200:203], v[48:51]
	v_mfma_f32_16x16x32_bf16 v[36:39], v[178:181], v[208:211], v[36:39]
	v_mfma_f32_16x16x32_bf16 v[32:35], v[186:189], v[208:211], v[32:35]
	v_mfma_f32_16x16x32_bf16 v[20:23], v[178:181], v[216:219], v[20:23]
	v_mfma_f32_16x16x32_bf16 v[16:19], v[186:189], v[216:219], v[16:19]
	v_mfma_f32_16x16x32_bf16 v[4:7], v[178:181], v[224:227], v[4:7]
	v_mfma_f32_16x16x32_bf16 v[0:3], v[186:189], v[224:227], v[0:3]
	v_mfma_f32_16x16x32_bf16 v[52:55], v[182:185], v[204:207], v[52:55]
	v_mfma_f32_16x16x32_bf16 v[48:51], v[196:199], v[204:207], v[48:51]
	v_mfma_f32_16x16x32_bf16 v[36:39], v[182:185], v[212:215], v[36:39]
	v_mfma_f32_16x16x32_bf16 v[32:35], v[196:199], v[212:215], v[32:35]
	v_mfma_f32_16x16x32_bf16 v[20:23], v[182:185], v[220:223], v[20:23]
	v_mfma_f32_16x16x32_bf16 v[16:19], v[196:199], v[220:223], v[16:19]
	v_mfma_f32_16x16x32_bf16 v[4:7], v[182:185], v[228:231], v[4:7]
	v_mfma_f32_16x16x32_bf16 v[0:3], v[196:199], v[228:231], v[0:3]
	s_setprio 0
	s_barrier
	s_add_i32 s53, 0, 0x18000
	v_add_u32_e32 v132, s53, v151
	s_add_i32 s54, 0, 0x1c000
	ds_read_b128 v[162:165], v132
	ds_read_b128 v[166:169], v132 offset:1024
	ds_read_b128 v[170:173], v132 offset:2048
	ds_read_b128 v[174:177], v132 offset:3072
	v_add_u32_e32 v132, s54, v151
	ds_read_b128 v[178:181], v132
	ds_read_b128 v[182:185], v132 offset:1024
	ds_read_b128 v[186:189], v132 offset:2048
	ds_read_b128 v[196:199], v132 offset:3072
	s_mov_b32 m0, s40
	v_cndmask_b32_e32 v132, v140, v158, vcc
	ds_read_b128 v[200:203], v155 offset:32768
	ds_read_b128 v[204:207], v155 offset:33792
	ds_read_b128 v[208:211], v155 offset:34816
	ds_read_b128 v[212:215], v155 offset:35840
	ds_read_b128 v[216:219], v155 offset:36864
	ds_read_b128 v[220:223], v155 offset:37888
	ds_read_b128 v[224:227], v155 offset:38912
	ds_read_b128 v[228:231], v155 offset:39936
	global_load_lds_dwordx4 v132, s[30:31]
	v_cndmask_b32_e32 v132, v138, v159, vcc
	s_mov_b32 m0, s41
	s_nop 0
	global_load_lds_dwordx4 v132, s[30:31]
	s_waitcnt vmcnt(8)
	s_waitcnt lgkmcnt(0)
	s_barrier
	s_setprio 1
	s_waitcnt lgkmcnt(0)
	v_mfma_f32_16x16x32_bf16 v[124:127], v[162:165], v[200:203], v[124:127]
	v_mfma_f32_16x16x32_bf16 v[120:123], v[170:173], v[200:203], v[120:123]
	v_mfma_f32_16x16x32_bf16 v[108:111], v[162:165], v[208:211], v[108:111]
	v_mfma_f32_16x16x32_bf16 v[104:107], v[170:173], v[208:211], v[104:107]
	v_mfma_f32_16x16x32_bf16 v[92:95], v[162:165], v[216:219], v[92:95]
	v_mfma_f32_16x16x32_bf16 v[88:91], v[170:173], v[216:219], v[88:91]
	v_mfma_f32_16x16x32_bf16 v[76:79], v[162:165], v[224:227], v[76:79]
	v_mfma_f32_16x16x32_bf16 v[72:75], v[170:173], v[224:227], v[72:75]
	v_mfma_f32_16x16x32_bf16 v[124:127], v[166:169], v[204:207], v[124:127]
	v_mfma_f32_16x16x32_bf16 v[120:123], v[174:177], v[204:207], v[120:123]
	v_mfma_f32_16x16x32_bf16 v[108:111], v[166:169], v[212:215], v[108:111]
	v_mfma_f32_16x16x32_bf16 v[104:107], v[174:177], v[212:215], v[104:107]
	v_mfma_f32_16x16x32_bf16 v[92:95], v[166:169], v[220:223], v[92:95]
	v_mfma_f32_16x16x32_bf16 v[88:91], v[174:177], v[220:223], v[88:91]
	v_mfma_f32_16x16x32_bf16 v[76:79], v[166:169], v[228:231], v[76:79]
	v_mfma_f32_16x16x32_bf16 v[72:75], v[174:177], v[228:231], v[72:75]
	s_setprio 0
	s_setprio 1
	v_mfma_f32_16x16x32_bf16 v[116:119], v[178:181], v[200:203], v[116:119]
	v_mfma_f32_16x16x32_bf16 v[112:115], v[186:189], v[200:203], v[112:115]
	v_mfma_f32_16x16x32_bf16 v[100:103], v[178:181], v[208:211], v[100:103]
	v_mfma_f32_16x16x32_bf16 v[96:99], v[186:189], v[208:211], v[96:99]
	v_mfma_f32_16x16x32_bf16 v[84:87], v[178:181], v[216:219], v[84:87]
	v_mfma_f32_16x16x32_bf16 v[80:83], v[186:189], v[216:219], v[80:83]
	v_mfma_f32_16x16x32_bf16 v[68:71], v[178:181], v[224:227], v[68:71]
	v_mfma_f32_16x16x32_bf16 v[64:67], v[186:189], v[224:227], v[64:67]
	v_mfma_f32_16x16x32_bf16 v[116:119], v[182:185], v[204:207], v[116:119]
	v_mfma_f32_16x16x32_bf16 v[112:115], v[196:199], v[204:207], v[112:115]
	v_mfma_f32_16x16x32_bf16 v[100:103], v[182:185], v[212:215], v[100:103]
	v_mfma_f32_16x16x32_bf16 v[96:99], v[196:199], v[212:215], v[96:99]
	v_mfma_f32_16x16x32_bf16 v[84:87], v[182:185], v[220:223], v[84:87]
	v_mfma_f32_16x16x32_bf16 v[80:83], v[196:199], v[220:223], v[80:83]
	v_mfma_f32_16x16x32_bf16 v[68:71], v[182:185], v[228:231], v[68:71]
	v_mfma_f32_16x16x32_bf16 v[64:67], v[196:199], v[228:231], v[64:67]
	s_setprio 0
	s_barrier
	s_add_i32 s30, s53, s38
	v_lshl_add_u64 v[190:191], v[190:191], 0, s[12:13]
	s_mov_b32 m0, s30
	ds_read_b128 v[200:203], v155 offset:49152
	ds_read_b128 v[204:207], v155 offset:50176
	ds_read_b128 v[208:211], v155 offset:51200
	ds_read_b128 v[212:215], v155 offset:52224
	ds_read_b128 v[216:219], v155 offset:53248
	ds_read_b128 v[220:223], v155 offset:54272
	ds_read_b128 v[224:227], v155 offset:55296
	ds_read_b128 v[228:231], v155 offset:56320
	global_load_lds_dwordx4 v[190:191], off
	s_add_i32 m0, s30, 0x2000
	s_add_u32 s28, s28, 0x40080
	v_lshl_add_u64 v[190:191], v[232:233], 0, s[12:13]
	s_addc_u32 s29, s29, 0
	s_add_i32 s30, s54, s38
	global_load_lds_dwordx4 v[190:191], off
	v_lshl_add_u64 v[190:191], s[28:29], 0, v[128:129]
	s_mov_b32 m0, s30
	s_nop 0
	global_load_lds_dwordx4 v[190:191], off
	v_lshl_add_u64 v[190:191], s[28:29], 0, v[130:131]
	s_add_i32 m0, s30, 0x2000
	s_nop 0
	global_load_lds_dwordx4 v[190:191], off
	v_lshl_add_u64 v[190:191], v[234:235], 0, s[12:13]
	s_mov_b32 m0, s43
	s_nop 0
	global_load_lds_dwordx4 v[190:191], off
	v_lshl_add_u64 v[190:191], v[236:237], 0, s[12:13]
	s_mov_b32 m0, s44
	s_nop 0
	global_load_lds_dwordx4 v[190:191], off
	s_waitcnt vmcnt(8)
	s_waitcnt lgkmcnt(0)
	s_barrier
	s_setprio 1
	s_waitcnt lgkmcnt(0)
	v_mfma_f32_16x16x32_bf16 v[60:63], v[162:165], v[200:203], v[60:63]
	v_mfma_f32_16x16x32_bf16 v[56:59], v[170:173], v[200:203], v[56:59]
	v_mfma_f32_16x16x32_bf16 v[44:47], v[162:165], v[208:211], v[44:47]
	v_mfma_f32_16x16x32_bf16 v[40:43], v[170:173], v[208:211], v[40:43]
	v_mfma_f32_16x16x32_bf16 v[28:31], v[162:165], v[216:219], v[28:31]
	v_mfma_f32_16x16x32_bf16 v[24:27], v[170:173], v[216:219], v[24:27]
	v_mfma_f32_16x16x32_bf16 v[12:15], v[162:165], v[224:227], v[12:15]
	v_mfma_f32_16x16x32_bf16 v[8:11], v[170:173], v[224:227], v[8:11]
	v_mfma_f32_16x16x32_bf16 v[60:63], v[166:169], v[204:207], v[60:63]
	v_mfma_f32_16x16x32_bf16 v[56:59], v[174:177], v[204:207], v[56:59]
	v_mfma_f32_16x16x32_bf16 v[44:47], v[166:169], v[212:215], v[44:47]
	v_mfma_f32_16x16x32_bf16 v[40:43], v[174:177], v[212:215], v[40:43]
	v_mfma_f32_16x16x32_bf16 v[28:31], v[166:169], v[220:223], v[28:31]
	v_mfma_f32_16x16x32_bf16 v[24:27], v[174:177], v[220:223], v[24:27]
	v_mfma_f32_16x16x32_bf16 v[12:15], v[166:169], v[228:231], v[12:15]
	v_mfma_f32_16x16x32_bf16 v[8:11], v[174:177], v[228:231], v[8:11]
	s_setprio 0
	s_setprio 1
	v_mfma_f32_16x16x32_bf16 v[52:55], v[178:181], v[200:203], v[52:55]
	v_mfma_f32_16x16x32_bf16 v[48:51], v[186:189], v[200:203], v[48:51]
	v_mfma_f32_16x16x32_bf16 v[36:39], v[178:181], v[208:211], v[36:39]
	v_mfma_f32_16x16x32_bf16 v[32:35], v[186:189], v[208:211], v[32:35]
	v_mfma_f32_16x16x32_bf16 v[20:23], v[178:181], v[216:219], v[20:23]
	v_mfma_f32_16x16x32_bf16 v[16:19], v[186:189], v[216:219], v[16:19]
	v_mfma_f32_16x16x32_bf16 v[4:7], v[178:181], v[224:227], v[4:7]
	v_mfma_f32_16x16x32_bf16 v[0:3], v[186:189], v[224:227], v[0:3]
	v_mfma_f32_16x16x32_bf16 v[52:55], v[182:185], v[204:207], v[52:55]
	v_mfma_f32_16x16x32_bf16 v[48:51], v[196:199], v[204:207], v[48:51]
	v_mfma_f32_16x16x32_bf16 v[36:39], v[182:185], v[212:215], v[36:39]
	v_mfma_f32_16x16x32_bf16 v[32:35], v[196:199], v[212:215], v[32:35]
	v_mfma_f32_16x16x32_bf16 v[20:23], v[182:185], v[220:223], v[20:23]
	v_mfma_f32_16x16x32_bf16 v[16:19], v[196:199], v[220:223], v[16:19]
	v_mfma_f32_16x16x32_bf16 v[4:7], v[182:185], v[228:231], v[4:7]
	v_mfma_f32_16x16x32_bf16 v[0:3], v[196:199], v[228:231], v[0:3]
	s_setprio 0
	s_barrier
	s_add_i32 s23, s23, 2
	s_add_u32 s26, s26, 0x100
	s_addc_u32 s27, s27, 0
	s_cmp_gt_u32 s23, 13
	s_cbranch_scc0 .LBB0_1078
	s_and_b64 vcc, exec, s[16:17]
	s_cbranch_vccz .LBB0_1081
	s_barrier
